# seams 8-11 as 4-workgroup row-panel barriers (panel chains P8..P12 run independently)
# speedup vs baseline: 1.0224x; 1.0113x over previous
; __device__ __forceinline__ unsigned xb_ld(unsigned* p)              { return __hip_atomic_load(p, __ATOMIC_RELAXED, __HIP_MEMORY_SCOPE_AGENT); }
; __device__ __forceinline__ unsigned xb_add(unsigned* p, unsigned v) { return __hip_atomic_fetch_add(p, v, __ATOMIC_RELAXED, __HIP_MEMORY_SCOPE_AGENT); }
; #define XB_SPIN(cond, bar) do { unsigned _sp = 0; while (cond) { __builtin_amdgcn_s_sleep(1); \
;     if ((++_sp & 255u) == 0u) { if (xb_ld(&(bar)[XB_TMO])) break; if (_sp > XB_SPIN_CAP) { atomicAdd(&(bar)[XB_TMO], 1u); break; } } } } while (0)
; #define SEAM(k) do { if (IN(k) && IN((k) + 1)) xcd_barrier(bar); } while (0)
; __device__ __forceinline__ void xcd_barrier(const XcdBarrier& b) {
;     asm volatile("s_waitcnt vmcnt(0)" ::: "memory");
;     __syncthreads();
;     if (threadIdx.x == 0) {
;         unsigned* bar = b.bar;
;         __builtin_amdgcn_s_waitcnt(0);
;         unsigned nloc = b.st[0], nx = b.st[1];
;         if (nloc == 0u) { xcd_barrier_complete(bar, b.x, nloc, nx); b.st[0] = nloc; b.st[1] = nx; }
;         const unsigned old = xb_add(&bar[XB_XSUB(b.x)], 1u);
;         const unsigned gen = old / nloc;
;         if (old + 1u == (gen + 1u) * nloc) {
;             __builtin_amdgcn_fence(__ATOMIC_RELEASE, "agent");
;             asm volatile("s_waitcnt vmcnt(0)" ::: "memory");
;             const unsigned og = xb_add(&bar[XB_TOP], 1u);
;             const unsigned tg = og / nx;
;             if (og + 1u == (tg + 1u) * nx) xb_add(&bar[XB_TOPGEN], 1u);
;             else XB_SPIN(xb_ld(&bar[XB_TOPGEN]) == tg, bar);
;             __builtin_amdgcn_fence(__ATOMIC_ACQUIRE, "agent");
;             xb_add(&bar[XB_XGEN(b.x)], 1u);
;             asm volatile("s_waitcnt vmcnt(0)" ::: "memory");
;         } else {
;             XB_SPIN(xb_ld(&bar[XB_XGEN(b.x)]) == gen, bar);
;             __builtin_amdgcn_fence(__ATOMIC_ACQUIRE, "agent");
;             asm volatile("s_waitcnt vmcnt(0)" ::: "memory");
;         }
;     }
;     __syncthreads();
; }
; __global__ void __launch_bounds__(NWAVES * 64, 2) mega_fwd(Args args) {
;     ...
;     SEAM(8);
;     if (IN(9)) { pg8::Gemm g{MG, Wout, M, DM, DM, DM, DM, 0, 0, 1}; pg8::StaticOrder S; S.init(M, DM, 1, G, bx);
;         pg8::EpiResid<true> E{nullptr, XB, ss2, 1.0f}; pg8::gemm_phase<pg8::EpiResid<true>, true>(lds, g, S, E); }
.LBB0_1138:
	s_cmp_gt_i32 s85, 9
	s_cselect_b64 s[0:1], -1, 0
	s_and_b64 s[2:3], s[4:5], s[0:1]
	s_andn2_b64 vcc, exec, s[2:3]
	s_cbranch_vccnz .LBB0_1192
	s_waitcnt vmcnt(0)
	s_waitcnt vmcnt(0) lgkmcnt(0)
	s_barrier
	s_and_saveexec_b64 s[2:3], s[74:75]
	s_cbranch_execz .LBB0_1191
	s_and_b32 s4, s88, 7
	s_lshl_b32 s4, s4, 3
	s_bfe_u32 s5, s88, 0x30003
	s_or_b32 s4, s4, s5
	s_lshl_b32 s4, s4, 8
	s_add_u32 s6, s66, 0xfd09000
	s_addc_u32 s7, s67, 0
	v_mov_b32_e32 v1, s4
	v_mov_b32_e32 v2, 1
	global_atomic_add v1, v2, s[6:7]
	v_mov_b32_e32 v5, 0x5000
	global_atomic_add v5, v2, s[6:7]
	s_movk_i32 s5, 4
	s_mov_b32 s8, 0

; __device__ __forceinline__ unsigned xb_ld(unsigned* p)              { return __hip_atomic_load(p, __ATOMIC_RELAXED, __HIP_MEMORY_SCOPE_AGENT); }
; __device__ __forceinline__ unsigned xb_add(unsigned* p, unsigned v) { return __hip_atomic_fetch_add(p, v, __ATOMIC_RELAXED, __HIP_MEMORY_SCOPE_AGENT); }
; #define XB_SPIN(cond, bar) do { unsigned _sp = 0; while (cond) { __builtin_amdgcn_s_sleep(1); \
;     if ((++_sp & 255u) == 0u) { if (xb_ld(&(bar)[XB_TMO])) break; if (_sp > XB_SPIN_CAP) { atomicAdd(&(bar)[XB_TMO], 1u); break; } } } } while (0)
; #define SEAM(k) do { if (IN(k) && IN((k) + 1)) xcd_barrier(bar); } while (0)
; __device__ __forceinline__ void xcd_barrier(const XcdBarrier& b) {
;     asm volatile("s_waitcnt vmcnt(0)" ::: "memory");
;     __syncthreads();
;     if (threadIdx.x == 0) {
;         unsigned* bar = b.bar;
;         __builtin_amdgcn_s_waitcnt(0);
;         unsigned nloc = b.st[0], nx = b.st[1];
;         if (nloc == 0u) { xcd_barrier_complete(bar, b.x, nloc, nx); b.st[0] = nloc; b.st[1] = nx; }
;         const unsigned old = xb_add(&bar[XB_XSUB(b.x)], 1u);
;         const unsigned gen = old / nloc;
;         if (old + 1u == (gen + 1u) * nloc) {
;             __builtin_amdgcn_fence(__ATOMIC_RELEASE, "agent");
;             asm volatile("s_waitcnt vmcnt(0)" ::: "memory");
;             const unsigned og = xb_add(&bar[XB_TOP], 1u);
;             const unsigned tg = og / nx;
;             if (og + 1u == (tg + 1u) * nx) xb_add(&bar[XB_TOPGEN], 1u);
;             else XB_SPIN(xb_ld(&bar[XB_TOPGEN]) == tg, bar);
;             __builtin_amdgcn_fence(__ATOMIC_ACQUIRE, "agent");
;             xb_add(&bar[XB_XGEN(b.x)], 1u);
;             asm volatile("s_waitcnt vmcnt(0)" ::: "memory");
;         } else {
;             XB_SPIN(xb_ld(&bar[XB_XGEN(b.x)]) == gen, bar);
;             __builtin_amdgcn_fence(__ATOMIC_ACQUIRE, "agent");
;             asm volatile("s_waitcnt vmcnt(0)" ::: "memory");
;         }
;     }
;     __syncthreads();
; }
; __global__ void __launch_bounds__(NWAVES * 64, 2) mega_fwd(Args args) {
;     ...
;     SEAM(9);
;     if (IN(10)) { pg8::Gemm g{XB, W2gu, M, 2 * FF, DM, DM, DM, 0, 0, 1}; pg8::StaticOrder S; S.init(M, 2 * FF, 1, G, bx);
;         pg8::EpiSwiglu E{ss2, ACT}; pg8::gemm_phase<pg8::EpiSwiglu, true>(lds, g, S, E);
.LBB0_1235:
	s_cmp_gt_i32 s85, 10
	s_cselect_b64 s[2:3], -1, 0
	s_and_b64 s[0:1], s[0:1], s[2:3]
	s_andn2_b64 vcc, exec, s[0:1]
	s_cbranch_vccnz .LBB0_1289
	s_waitcnt vmcnt(0)
	s_waitcnt vmcnt(0) lgkmcnt(0)
	s_barrier
	s_and_saveexec_b64 s[0:1], s[74:75]
	s_cbranch_execz .LBB0_1288
	s_and_b32 s4, s88, 7
	s_lshl_b32 s4, s4, 3
	s_bfe_u32 s5, s88, 0x30003
	s_or_b32 s4, s4, s5
	s_lshl_b32 s4, s4, 8
	s_add_u32 s6, s66, 0xfd09000
	s_addc_u32 s7, s67, 0
	v_mov_b32_e32 v1, s4
	v_mov_b32_e32 v2, 1
	global_atomic_add v1, v2, s[6:7]
	s_movk_i32 s5, 8
	s_mov_b32 s8, 0
.Lls9_spin:
	global_load_dword v3, v1, s[6:7] sc1
	v_mov_b32_e32 v5, 0x5000
	global_load_dword v6, v5, s[6:7] sc1
	s_waitcnt vmcnt(0)
	v_readfirstlane_b32 s9, v3
	v_readfirstlane_b32 s4, v6
	s_nop 3
	s_cmp_ge_u32 s9, s5
	s_cselect_b32 s9, 1, 0
	s_cmp_ge_u32 s4, s86
	s_cselect_b32 s4, 1, 0
	s_and_b32 s9, s9, s4
	s_cmp_lg_u32 s9, 0
	s_cbranch_scc1 .Lls9_ok
	s_sleep 1
	s_add_i32 s8, s8, 1
	s_cmp_lt_u32 s8, 0x20000
	s_cbranch_scc1 .Lls9_spin

; __device__ __forceinline__ unsigned xb_ld(unsigned* p)              { return __hip_atomic_load(p, __ATOMIC_RELAXED, __HIP_MEMORY_SCOPE_AGENT); }
; __device__ __forceinline__ unsigned xb_add(unsigned* p, unsigned v) { return __hip_atomic_fetch_add(p, v, __ATOMIC_RELAXED, __HIP_MEMORY_SCOPE_AGENT); }
; #define XB_SPIN(cond, bar) do { unsigned _sp = 0; while (cond) { __builtin_amdgcn_s_sleep(1); \
;     if ((++_sp & 255u) == 0u) { if (xb_ld(&(bar)[XB_TMO])) break; if (_sp > XB_SPIN_CAP) { atomicAdd(&(bar)[XB_TMO], 1u); break; } } } } while (0)
; #define SEAM(k) do { if (IN(k) && IN((k) + 1)) xcd_barrier(bar); } while (0)
; __device__ __forceinline__ void xcd_barrier(const XcdBarrier& b) {
;     asm volatile("s_waitcnt vmcnt(0)" ::: "memory");
;     __syncthreads();
;     if (threadIdx.x == 0) {
;         unsigned* bar = b.bar;
;         __builtin_amdgcn_s_waitcnt(0);
;         unsigned nloc = b.st[0], nx = b.st[1];
;         if (nloc == 0u) { xcd_barrier_complete(bar, b.x, nloc, nx); b.st[0] = nloc; b.st[1] = nx; }
;         const unsigned old = xb_add(&bar[XB_XSUB(b.x)], 1u);
;         const unsigned gen = old / nloc;
;         if (old + 1u == (gen + 1u) * nloc) {
;             __builtin_amdgcn_fence(__ATOMIC_RELEASE, "agent");
;             asm volatile("s_waitcnt vmcnt(0)" ::: "memory");
;             const unsigned og = xb_add(&bar[XB_TOP], 1u);
;             const unsigned tg = og / nx;
;             if (og + 1u == (tg + 1u) * nx) xb_add(&bar[XB_TOPGEN], 1u);
;             else XB_SPIN(xb_ld(&bar[XB_TOPGEN]) == tg, bar);
;             __builtin_amdgcn_fence(__ATOMIC_ACQUIRE, "agent");
;             xb_add(&bar[XB_XGEN(b.x)], 1u);
;             asm volatile("s_waitcnt vmcnt(0)" ::: "memory");
;         } else {
;             XB_SPIN(xb_ld(&bar[XB_XGEN(b.x)]) == gen, bar);
;             __builtin_amdgcn_fence(__ATOMIC_ACQUIRE, "agent");
;             asm volatile("s_waitcnt vmcnt(0)" ::: "memory");
;         }
;     }
;     __syncthreads();
; }
; __global__ void __launch_bounds__(NWAVES * 64, 2) mega_fwd(Args args) {
;     ...
;     SEAM(10);
;     if (IN(11)) { pg8::Gemm g{ACT, W2d, M, DM, FF, 64, FF, 0, 0, 1, (size_t)256 * 64 * 2, (size_t)(FF / 64) * 256 * 64 * 2}; pg8::StaticOrder S; S.init(M, DM, 1, G, bx);
;         pg8::EpiResid<true> E{nullptr, XB, ss3, 0.5f}; pg8::gemm_phase<pg8::EpiResid<true>, true>(lds, g, S, E); }
.LBB0_1327:
	s_cmp_gt_i32 s85, 11
	s_cselect_b64 s[2:3], -1, 0
	s_and_b64 s[0:1], s[0:1], s[2:3]
	v_readlane_b32 s48, v252, 22
	s_andn2_b64 vcc, exec, s[0:1]
	v_readlane_b32 s49, v252, 23
	s_cbranch_vccnz .LBB0_1381
	s_waitcnt vmcnt(0)
	s_waitcnt vmcnt(0) lgkmcnt(0)
	s_barrier
	s_and_saveexec_b64 s[0:1], s[74:75]
	s_cbranch_execz .LBB0_1380
	s_and_b32 s4, s88, 7
	s_lshl_b32 s4, s4, 3
	s_bfe_u32 s5, s88, 0x30003
	s_or_b32 s4, s4, s5
	s_lshl_b32 s4, s4, 8
	s_add_u32 s6, s66, 0xfd09000
	s_addc_u32 s7, s67, 0
	v_mov_b32_e32 v1, s4
	v_mov_b32_e32 v2, 1
	global_atomic_add v1, v2, s[6:7]
	s_movk_i32 s5, 12
	s_mov_b32 s8, 0

; __device__ __forceinline__ unsigned xb_ld(unsigned* p)              { return __hip_atomic_load(p, __ATOMIC_RELAXED, __HIP_MEMORY_SCOPE_AGENT); }
; __device__ __forceinline__ unsigned xb_add(unsigned* p, unsigned v) { return __hip_atomic_fetch_add(p, v, __ATOMIC_RELAXED, __HIP_MEMORY_SCOPE_AGENT); }
; #define XB_SPIN(cond, bar) do { unsigned _sp = 0; while (cond) { __builtin_amdgcn_s_sleep(1); \
;     if ((++_sp & 255u) == 0u) { if (xb_ld(&(bar)[XB_TMO])) break; if (_sp > XB_SPIN_CAP) { atomicAdd(&(bar)[XB_TMO], 1u); break; } } } } while (0)
; #define SEAM(k) do { if (IN(k) && IN((k) + 1)) xcd_barrier(bar); } while (0)
; __device__ __forceinline__ void xcd_barrier(const XcdBarrier& b) {
;     asm volatile("s_waitcnt vmcnt(0)" ::: "memory");
;     __syncthreads();
;     if (threadIdx.x == 0) {
;         unsigned* bar = b.bar;
;         __builtin_amdgcn_s_waitcnt(0);
;         unsigned nloc = b.st[0], nx = b.st[1];
;         if (nloc == 0u) { xcd_barrier_complete(bar, b.x, nloc, nx); b.st[0] = nloc; b.st[1] = nx; }
;         const unsigned old = xb_add(&bar[XB_XSUB(b.x)], 1u);
;         const unsigned gen = old / nloc;
;         if (old + 1u == (gen + 1u) * nloc) {
;             __builtin_amdgcn_fence(__ATOMIC_RELEASE, "agent");
;             asm volatile("s_waitcnt vmcnt(0)" ::: "memory");
;             const unsigned og = xb_add(&bar[XB_TOP], 1u);
;             const unsigned tg = og / nx;
;             if (og + 1u == (tg + 1u) * nx) xb_add(&bar[XB_TOPGEN], 1u);
;             else XB_SPIN(xb_ld(&bar[XB_TOPGEN]) == tg, bar);
;             __builtin_amdgcn_fence(__ATOMIC_ACQUIRE, "agent");
;             xb_add(&bar[XB_XGEN(b.x)], 1u);
;             asm volatile("s_waitcnt vmcnt(0)" ::: "memory");
;         } else {
;             XB_SPIN(xb_ld(&bar[XB_XGEN(b.x)]) == gen, bar);
;             __builtin_amdgcn_fence(__ATOMIC_ACQUIRE, "agent");
;             asm volatile("s_waitcnt vmcnt(0)" ::: "memory");
;         }
;     }
;     __syncthreads();
; }
; __global__ void __launch_bounds__(NWAVES * 64, 2) mega_fwd(Args args) {
;     ...
;     SEAM(11);
;     if (IN(12)) { pg8::StaticOrder S; S.init(M, DM, 1, G, bx);
;         { pg8::Gemm g{XB, Wpg, M, DM, DM, DM, DM, 0, 0, 1}; pg8::EpiPle2 E{ss3, PTMP, XB, out}; pg8::gemm_phase<pg8::EpiPle2, true>(lds, g, S, E); } }
.LBB0_1428:
	s_cmp_gt_i32 s85, 12
	s_cselect_b64 s[2:3], -1, 0
	s_and_b64 s[0:1], s[0:1], s[2:3]
	s_andn2_b64 vcc, exec, s[0:1]
	s_cbranch_vccnz .LBB0_1482
	s_waitcnt vmcnt(0)
	s_waitcnt vmcnt(0) lgkmcnt(0)
	s_barrier
	s_and_saveexec_b64 s[0:1], s[74:75]
	s_cbranch_execz .LBB0_1481
	s_and_b32 s4, s88, 7
	s_lshl_b32 s4, s4, 3
	s_bfe_u32 s5, s88, 0x30003
	s_or_b32 s4, s4, s5
	s_lshl_b32 s4, s4, 8
	s_add_u32 s6, s66, 0xfd09000
	s_addc_u32 s7, s67, 0
	v_mov_b32_e32 v1, s4
	v_mov_b32_e32 v2, 1
	global_atomic_add v1, v2, s[6:7]
	s_movk_i32 s5, 16
	s_mov_b32 s8, 0
